# v52 + retention d-half-0 staging: Q/K rows written and second-half loads issued before the V scaling / state conversion
# speedup vs baseline: 1.0094x; 1.0021x over previous
.Lret_a_done:
	v_mov_b32_e32 v232, v227
	v_mov_b32_e32 v234, v193
	v_mov_b32_e32 v197, v202
	v_mov_b32_e32 v233, v201
	s_and_b64 vcc, exec, s[54:55]
	s_barrier
	s_not_b64 s[16:17], s[54:55]
	s_and_b64 vcc, exec, s[54:55]
	s_cbranch_vccz .Lra_noq
	v_mul_u32_u24_e32 v2, 0x110, v197
	v_add_u32_e32 v2, v192, v2
	ds_write_b128 v2, v[156:159]
	ds_write_b128 v2, v[152:155] offset:8704
	ds_write_b128 v2, v[148:151] offset:17408
	ds_write_b128 v2, v[144:147] offset:26112
.Lra_noq:
	ds_write_b128 v249, v[184:187] offset:34816
	ds_write_b128 v249, v[188:191] offset:43008
	ds_write_b128 v249, v[180:183] offset:51200
	ds_write_b128 v249, v[176:179] offset:59392
	s_and_b64 vcc, exec, s[54:55]
	s_cselect_b64 s[14:15], s[40:41], s[30:31]
	s_lshl_b32 s28, s18, 7
	s_ashr_i32 s34, s28, 31
	s_add_u32 s18, s14, s28
	v_mov_b32_e32 v1, v202
	s_addc_u32 s19, s15, s34
	s_lshl_b64 s[14:15], s[18:19], 11
	v_sub_u32_e32 v2, 0x7f, v1
	v_cndmask_b32_e64 v2, v2, v1, s[44:45]
	s_add_u32 s14, s38, s14
	v_lshl_or_b32 v2, v2, 10, v203
	s_addc_u32 s15, s39, s15
	s_and_b64 vcc, exec, s[16:17]
	v_ashrrev_i32_e32 v3, 31, v2
	s_cbranch_vccnz .Lra_l1
	v_lshl_add_u64 v[4:5], v[2:3], 1, s[14:15]
	global_load_dwordx4 v[156:159], v[4:5], off offset:256

.Lra_l4:
	v_lshl_add_u64 v[2:3], v[2:3], 1, s[18:19]
	global_load_dwordx4 v[176:179], v[2:3], off offset:256
	s_and_b64 vcc, exec, s[54:55]
	s_cbranch_vccz .LBB0_898
	s_waitcnt lgkmcnt(0)
	v_mad_u64_u32 v[2:3], s[14:15], v197, s68, v[192:193]
.LBB0_898:
	v_add_u32_e32 v1, 1, v197
	v_cvt_f32_i32_e32 v1, v1
	v_mul_lo_u32 v6, v197, s68
	s_waitcnt lgkmcnt(0)
	v_lshlrev_b32_e32 v2, 16, v160
	v_and_b32_e32 v3, 0xffff0000, v160
	v_mul_f32_e64 v1, -v232, v1
	v_exp_f32_e32 v1, v1
	v_add_u32_e32 v228, v192, v6
	v_and_b32_e32 v4, 0xffff0000, v161
	v_mul_f32_e32 v1, 0x3d800000, v1
	v_mul_f32_e32 v2, v1, v2
	v_mul_f32_e32 v3, v1, v3
	v_cvt_pk_bf16_f32 v2, v2, v3
	v_lshlrev_b32_e32 v3, 16, v161
	v_mul_f32_e32 v3, v1, v3
	v_mul_f32_e32 v4, v1, v4
	v_cvt_pk_bf16_f32 v3, v3, v4
	v_lshlrev_b32_e32 v4, 16, v162
	v_and_b32_e32 v5, 0xffff0000, v162
	v_mul_f32_e32 v4, v1, v4
	v_mul_f32_e32 v5, v1, v5
	v_cvt_pk_bf16_f32 v4, v4, v5
	v_lshlrev_b32_e32 v5, 16, v163
	v_and_b32_e32 v7, 0xffff0000, v163
	v_mul_f32_e32 v5, v1, v5
	v_mul_f32_e32 v1, v1, v7
	v_cvt_pk_bf16_f32 v5, v5, v1
	v_add_u32_e32 v1, 0x11000, v249
	ds_write_b128 v1, v[2:5]
	v_cndmask_b32_e64 v2, 0, 1, s[54:55]
	v_cmp_ne_u32_e64 s[16:17], 1, v2
	s_andn2_b64 vcc, exec, s[54:55]
	v_add_u32_e32 v231, 32, v197
	s_cbranch_vccnz .LBB0_900
	v_mad_u64_u32 v[2:3], s[14:15], v231, s68, v[192:193]
.LBB0_900:
	v_add_u32_e32 v2, 33, v197
	v_cvt_f32_i32_e32 v2, v2
	v_lshlrev_b32_e32 v3, 16, v164
	v_and_b32_e32 v4, 0xffff0000, v164
	v_mul_f32_e64 v2, -v232, v2
	v_exp_f32_e32 v2, v2
	v_lshlrev_b32_e32 v5, 16, v165
	v_and_b32_e32 v7, 0xffff0000, v167
	s_and_b64 vcc, exec, s[16:17]
	v_mul_f32_e32 v6, 0x3d800000, v2
	v_mul_f32_e32 v2, v6, v3
	v_mul_f32_e32 v3, v6, v4
	v_cvt_pk_bf16_f32 v2, v2, v3
	v_and_b32_e32 v3, 0xffff0000, v165
	v_mul_f32_e32 v4, v6, v5
	v_mul_f32_e32 v3, v6, v3
	v_cvt_pk_bf16_f32 v3, v4, v3
	v_lshlrev_b32_e32 v4, 16, v166
	v_and_b32_e32 v5, 0xffff0000, v166
	v_mul_f32_e32 v4, v6, v4
	v_mul_f32_e32 v5, v6, v5
	v_cvt_pk_bf16_f32 v4, v4, v5
	v_lshlrev_b32_e32 v5, 16, v167
	v_mul_f32_e32 v5, v6, v5
	v_add_u32_e32 v230, 64, v197
	v_mul_f32_e32 v6, v6, v7
	v_cvt_pk_bf16_f32 v5, v5, v6
	ds_write_b128 v1, v[2:5] offset:8192
	s_cbranch_vccnz .LBB0_902
	v_mad_u64_u32 v[2:3], s[14:15], v230, s68, v[192:193]
.LBB0_902:
	v_add_u32_e32 v2, 0x41, v197
	v_cvt_f32_i32_e32 v2, v2
	v_lshlrev_b32_e32 v3, 16, v168
	v_and_b32_e32 v4, 0xffff0000, v168
	v_mul_f32_e64 v2, -v232, v2
	v_exp_f32_e32 v2, v2
	v_lshlrev_b32_e32 v5, 16, v169
	v_and_b32_e32 v7, 0xffff0000, v171
	s_and_b64 vcc, exec, s[16:17]
	v_mul_f32_e32 v6, 0x3d800000, v2
	v_mul_f32_e32 v2, v6, v3
	v_mul_f32_e32 v3, v6, v4
	v_cvt_pk_bf16_f32 v2, v2, v3
	v_and_b32_e32 v3, 0xffff0000, v169
	v_mul_f32_e32 v4, v6, v5
	v_mul_f32_e32 v3, v6, v3
	v_cvt_pk_bf16_f32 v3, v4, v3
	v_lshlrev_b32_e32 v4, 16, v170
	v_and_b32_e32 v5, 0xffff0000, v170
	v_mul_f32_e32 v4, v6, v4
	v_mul_f32_e32 v5, v6, v5
	v_cvt_pk_bf16_f32 v4, v4, v5
	v_lshlrev_b32_e32 v5, 16, v171
	v_mul_f32_e32 v5, v6, v5
	v_add_u32_e32 v229, 0x60, v197
	v_mul_f32_e32 v6, v6, v7
	v_cvt_pk_bf16_f32 v5, v5, v6
	ds_write_b128 v1, v[2:5] offset:16384
	s_cbranch_vccnz .LBB0_904
	v_mad_u64_u32 v[2:3], s[14:15], v229, s68, v[192:193]
.LBB0_904:
	v_add_u32_e32 v2, 0x61, v197
	v_cvt_f32_i32_e32 v2, v2
	v_lshlrev_b32_e32 v3, 16, v172
	v_and_b32_e32 v4, 0xffff0000, v172
	v_mul_f32_e64 v2, -v232, v2
	v_exp_f32_e32 v2, v2
	v_lshlrev_b32_e32 v5, 16, v173
	v_and_b32_e32 v7, 0xffff0000, v175
	s_and_b64 vcc, exec, s[54:55]
	v_mul_f32_e32 v6, 0x3d800000, v2
	v_mul_f32_e32 v2, v6, v3
	v_mul_f32_e32 v3, v6, v4
	v_cvt_pk_bf16_f32 v2, v2, v3
	v_and_b32_e32 v3, 0xffff0000, v173
	v_mul_f32_e32 v4, v6, v5
	v_mul_f32_e32 v3, v6, v3
	v_cvt_pk_bf16_f32 v3, v4, v3
	v_lshlrev_b32_e32 v4, 16, v174
	v_and_b32_e32 v5, 0xffff0000, v174
	v_mul_f32_e32 v4, v6, v4
	v_mul_f32_e32 v5, v6, v5
	v_cvt_pk_bf16_f32 v4, v4, v5
	v_lshlrev_b32_e32 v5, 16, v175
	v_mul_f32_e32 v5, v6, v5
	s_mov_b64 s[14:15], s[30:31]
	v_mul_f32_e32 v6, v6, v7
	v_cvt_pk_bf16_f32 v5, v5, v6
	ds_write_b128 v1, v[2:5] offset:24576
	s_cbranch_vccz .LBB0_906
	v_cvt_pk_bf16_f32 v2, v64, v65
	v_cvt_pk_bf16_f32 v3, v66, v67
	ds_write_b64 v225, v[2:3]
	v_cvt_pk_bf16_f32 v2, v68, v69
	v_cvt_pk_bf16_f32 v3, v70, v71
	ds_write_b64 v225, v[2:3] offset:16
	v_cvt_pk_bf16_f32 v2, v72, v73
	v_cvt_pk_bf16_f32 v3, v74, v75
	ds_write_b64 v225, v[2:3] offset:32
	v_cvt_pk_bf16_f32 v2, v76, v77
	v_cvt_pk_bf16_f32 v3, v78, v79
	ds_write_b64 v225, v[2:3] offset:48
	v_cvt_pk_bf16_f32 v2, v48, v49
	v_cvt_pk_bf16_f32 v3, v50, v51
	ds_write_b64 v225, v[2:3] offset:64
	v_cvt_pk_bf16_f32 v2, v52, v53
	v_cvt_pk_bf16_f32 v3, v54, v55
	ds_write_b64 v225, v[2:3] offset:80
	v_cvt_pk_bf16_f32 v2, v56, v57
	v_cvt_pk_bf16_f32 v3, v58, v59
	s_mov_b64 s[14:15], s[40:41]
	ds_write_b64 v225, v[2:3] offset:96
	v_cvt_pk_bf16_f32 v2, v60, v61
	v_cvt_pk_bf16_f32 v3, v62, v63
	ds_write_b64 v225, v[2:3] offset:112
.LBB0_906:
	s_and_b64 vcc, exec, s[16:17]
	s_mov_b32 s33, 0
	s_waitcnt lgkmcnt(0)
	s_barrier
	v_sub_co_u32_e64 v1, s[14:15], s49, 1
	s_cbranch_vccnz .Lret_b0_ctx
	v_add_u32_e32 v14, 0x19800, v212
	s_and_b64 vcc, exec, s[2:3]
	s_cbranch_vccz .Lret_b0_c
	s_and_b64 vcc, exec, s[4:5]
	s_cbranch_vccz .Lret_b0_b
	ds_read_b128 v[2:5], v250
	ds_read_b128 v[6:9], v250 offset:8192
	ds_read_b128 v[10:13], v194
	v_xor_b32_e32 v15, 32, v250
	ds_read_b128 v[236:239], v15
	ds_read_b128 v[240:243], v15 offset:8192
	ds_read_b128 v[244:247], v194 offset:32
	v_xor_b32_e32 v15, 64, v250
	ds_read_b128 v[160:163], v15
	ds_read_b128 v[164:167], v15 offset:8192
	s_waitcnt lgkmcnt(5)
	v_mfma_f32_32x32x16_bf16 v[128:143], v[2:5], v[10:13], 0
	ds_read_b128 v[168:171], v194 offset:64
	v_mfma_f32_32x32x16_bf16 v[112:127], v[6:9], v[10:13], 0
	v_xor_b32_e32 v15, 0x60, v250
	ds_read_b128 v[2:5], v15
	ds_read_b128 v[6:9], v15 offset:8192
	s_waitcnt lgkmcnt(5)
	v_mfma_f32_32x32x16_bf16 v[128:143], v[236:239], v[244:247], v[128:143]
	ds_read_b128 v[10:13], v194 offset:96
	v_mfma_f32_32x32x16_bf16 v[112:127], v[240:243], v[244:247], v[112:127]
	v_xor_b32_e32 v15, 0x80, v250
	ds_read_b128 v[236:239], v15
	ds_read_b128 v[240:243], v15 offset:8192
	s_waitcnt lgkmcnt(5)
	v_mfma_f32_32x32x16_bf16 v[128:143], v[160:163], v[168:171], v[128:143]
	ds_read_b128 v[244:247], v194 offset:128
	v_mfma_f32_32x32x16_bf16 v[112:127], v[164:167], v[168:171], v[112:127]
	v_xor_b32_e32 v15, 0xa0, v250
	ds_read_b128 v[160:163], v15
	ds_read_b128 v[164:167], v15 offset:8192
	s_waitcnt lgkmcnt(5)
	v_mfma_f32_32x32x16_bf16 v[128:143], v[2:5], v[10:13], v[128:143]
	ds_read_b128 v[168:171], v194 offset:160
	v_mfma_f32_32x32x16_bf16 v[112:127], v[6:9], v[10:13], v[112:127]
	v_xor_b32_e32 v15, 0xc0, v250
	ds_read_b128 v[2:5], v15
	ds_read_b128 v[6:9], v15 offset:8192
	s_waitcnt lgkmcnt(5)
	v_mfma_f32_32x32x16_bf16 v[128:143], v[236:239], v[244:247], v[128:143]
	ds_read_b128 v[10:13], v194 offset:192
	v_mfma_f32_32x32x16_bf16 v[112:127], v[240:243], v[244:247], v[112:127]
	v_xor_b32_e32 v15, 0xe0, v250
	ds_read_b128 v[236:239], v15
	ds_read_b128 v[240:243], v15 offset:8192
	s_waitcnt lgkmcnt(5)
	v_mfma_f32_32x32x16_bf16 v[128:143], v[160:163], v[168:171], v[128:143]
	ds_read_b128 v[244:247], v194 offset:224
	v_mfma_f32_32x32x16_bf16 v[112:127], v[164:167], v[168:171], v[112:127]
	ds_read_b128 v[160:163], v14
	ds_read_b128 v[164:167], v195
	s_waitcnt lgkmcnt(5)
	v_mfma_f32_32x32x16_bf16 v[128:143], v[2:5], v[10:13], v[128:143]
	ds_read_b128 v[168:171], v195 offset:8704
	v_mfma_f32_32x32x16_bf16 v[112:127], v[6:9], v[10:13], v[112:127]
	ds_read_b128 v[2:5], v14 offset:32
	ds_read_b128 v[6:9], v195 offset:32
	s_waitcnt lgkmcnt(5)
	v_mfma_f32_32x32x16_bf16 v[128:143], v[236:239], v[244:247], v[128:143]
	ds_read_b128 v[10:13], v195 offset:8736
	v_mfma_f32_32x32x16_bf16 v[112:127], v[240:243], v[244:247], v[112:127]
	ds_read_b128 v[236:239], v14 offset:64
	ds_read_b128 v[240:243], v195 offset:64
	s_waitcnt lgkmcnt(5)
	v_mfma_f32_32x32x16_bf16 v[96:111], v[160:163], v[164:167], 0
	ds_read_b128 v[244:247], v195 offset:8768
	v_mfma_f32_32x32x16_bf16 v[80:95], v[160:163], v[168:171], 0
	ds_read_b128 v[160:163], v14 offset:96
	ds_read_b128 v[164:167], v195 offset:96
	s_waitcnt lgkmcnt(5)
	v_mfma_f32_32x32x16_bf16 v[96:111], v[2:5], v[6:9], v[96:111]
	ds_read_b128 v[168:171], v195 offset:8800
	v_mfma_f32_32x32x16_bf16 v[80:95], v[2:5], v[10:13], v[80:95]
	ds_read_b128 v[2:5], v14 offset:128
	ds_read_b128 v[6:9], v195 offset:128
	s_waitcnt lgkmcnt(5)
	v_mfma_f32_32x32x16_bf16 v[96:111], v[236:239], v[240:243], v[96:111]
	ds_read_b128 v[10:13], v195 offset:8832
	v_mfma_f32_32x32x16_bf16 v[80:95], v[236:239], v[244:247], v[80:95]
	ds_read_b128 v[236:239], v14 offset:160
	ds_read_b128 v[240:243], v195 offset:160
	s_waitcnt lgkmcnt(5)
	v_mfma_f32_32x32x16_bf16 v[96:111], v[160:163], v[164:167], v[96:111]
	ds_read_b128 v[244:247], v195 offset:8864
	v_mfma_f32_32x32x16_bf16 v[80:95], v[160:163], v[168:171], v[80:95]
	ds_read_b128 v[160:163], v14 offset:192
	ds_read_b128 v[164:167], v195 offset:192
	s_waitcnt lgkmcnt(5)
	v_mfma_f32_32x32x16_bf16 v[96:111], v[2:5], v[6:9], v[96:111]
	ds_read_b128 v[168:171], v195 offset:8896
	v_mfma_f32_32x32x16_bf16 v[80:95], v[2:5], v[10:13], v[80:95]
	ds_read_b128 v[2:5], v14 offset:224
	ds_read_b128 v[6:9], v195 offset:224
	s_waitcnt lgkmcnt(5)
	v_mfma_f32_32x32x16_bf16 v[96:111], v[236:239], v[240:243], v[96:111]
	ds_read_b128 v[10:13], v195 offset:8928
	v_mfma_f32_32x32x16_bf16 v[80:95], v[236:239], v[244:247], v[80:95]
	ds_read_b64_tr_b16 v[236:237], v251
	ds_read_b64_tr_b16 v[238:239], v252
	ds_read_b64_tr_b16 v[244:245], v235
	s_waitcnt lgkmcnt(6)
	v_mfma_f32_32x32x16_bf16 v[96:111], v[160:163], v[164:167], v[96:111]
	ds_read_b64_tr_b16 v[246:247], v255
	ds_read_b64_tr_b16 v[240:241], v253
	ds_read_b64_tr_b16 v[242:243], v200
	v_mfma_f32_32x32x16_bf16 v[80:95], v[160:163], v[168:171], v[80:95]
	ds_read_b64_tr_b16 v[160:161], v251 offset:4096
	ds_read_b64_tr_b16 v[162:163], v252 offset:4096
	ds_read_b64_tr_b16 v[168:169], v235 offset:4096
	s_waitcnt lgkmcnt(9)
	v_mfma_f32_32x32x16_bf16 v[96:111], v[2:5], v[6:9], v[96:111]
	ds_read_b64_tr_b16 v[170:171], v255 offset:4096
	ds_read_b64_tr_b16 v[164:165], v253 offset:4096
	ds_read_b64_tr_b16 v[166:167], v200 offset:4096
	v_mfma_f32_32x32x16_bf16 v[80:95], v[2:5], v[10:13], v[80:95]
	ds_read_b64_tr_b16 v[2:3], v251 offset:8192
	ds_read_b64_tr_b16 v[4:5], v252 offset:8192
	ds_read_b64_tr_b16 v[10:11], v235 offset:8192
	s_waitcnt lgkmcnt(9)
	v_mfma_f32_32x32x16_bf16 v[64:79], v[236:239], v[244:247], v[64:79]
	ds_read_b64_tr_b16 v[12:13], v255 offset:8192
	ds_read_b64_tr_b16 v[6:7], v253 offset:8192
	ds_read_b64_tr_b16 v[8:9], v200 offset:8192
	v_mfma_f32_32x32x16_bf16 v[48:63], v[240:243], v[244:247], v[48:63]
	ds_read_b64_tr_b16 v[236:237], v251 offset:12288
	ds_read_b64_tr_b16 v[238:239], v252 offset:12288
	ds_read_b64_tr_b16 v[244:245], v235 offset:12288
	s_waitcnt lgkmcnt(9)
	v_mfma_f32_32x32x16_bf16 v[64:79], v[160:163], v[168:171], v[64:79]
	ds_read_b64_tr_b16 v[246:247], v255 offset:12288
	ds_read_b64_tr_b16 v[240:241], v253 offset:12288
	ds_read_b64_tr_b16 v[242:243], v200 offset:12288
	v_mfma_f32_32x32x16_bf16 v[48:63], v[164:167], v[168:171], v[48:63]
	ds_read_b64_tr_b16 v[160:161], v251 offset:16384
	ds_read_b64_tr_b16 v[162:163], v252 offset:16384
	ds_read_b64_tr_b16 v[168:169], v235 offset:16384
	s_waitcnt lgkmcnt(9)
	v_mfma_f32_32x32x16_bf16 v[64:79], v[2:5], v[10:13], v[64:79]
	ds_read_b64_tr_b16 v[170:171], v255 offset:16384
	ds_read_b64_tr_b16 v[164:165], v253 offset:16384
	ds_read_b64_tr_b16 v[166:167], v200 offset:16384
	v_mfma_f32_32x32x16_bf16 v[48:63], v[6:9], v[10:13], v[48:63]
	ds_read_b64_tr_b16 v[2:3], v251 offset:20480
	ds_read_b64_tr_b16 v[4:5], v252 offset:20480
	ds_read_b64_tr_b16 v[10:11], v235 offset:20480
	s_waitcnt lgkmcnt(9)
	v_mfma_f32_32x32x16_bf16 v[64:79], v[236:239], v[244:247], v[64:79]
	ds_read_b64_tr_b16 v[12:13], v255 offset:20480
	ds_read_b64_tr_b16 v[6:7], v253 offset:20480
	ds_read_b64_tr_b16 v[8:9], v200 offset:20480
	v_mfma_f32_32x32x16_bf16 v[48:63], v[240:243], v[244:247], v[48:63]
	ds_read_b64_tr_b16 v[236:237], v251 offset:24576
	ds_read_b64_tr_b16 v[238:239], v252 offset:24576
	ds_read_b64_tr_b16 v[244:245], v235 offset:24576
	s_waitcnt lgkmcnt(9)
	v_mfma_f32_32x32x16_bf16 v[64:79], v[160:163], v[168:171], v[64:79]
	ds_read_b64_tr_b16 v[246:247], v255 offset:24576
	ds_read_b64_tr_b16 v[240:241], v253 offset:24576
	ds_read_b64_tr_b16 v[242:243], v200 offset:24576
	v_mfma_f32_32x32x16_bf16 v[48:63], v[164:167], v[168:171], v[48:63]
	ds_read_b64_tr_b16 v[160:161], v251 offset:28672
	ds_read_b64_tr_b16 v[162:163], v252 offset:28672
	ds_read_b64_tr_b16 v[168:169], v235 offset:28672
	s_waitcnt lgkmcnt(9)
	v_mfma_f32_32x32x16_bf16 v[64:79], v[2:5], v[10:13], v[64:79]
	ds_read_b64_tr_b16 v[170:171], v255 offset:28672
	ds_read_b64_tr_b16 v[164:165], v253 offset:28672
	ds_read_b64_tr_b16 v[166:167], v200 offset:28672
	v_mfma_f32_32x32x16_bf16 v[48:63], v[6:9], v[10:13], v[48:63]
	s_waitcnt lgkmcnt(6)
	v_mfma_f32_32x32x16_bf16 v[64:79], v[236:239], v[244:247], v[64:79]
	v_mfma_f32_32x32x16_bf16 v[48:63], v[240:243], v[244:247], v[48:63]
	s_waitcnt lgkmcnt(0)
	v_mfma_f32_32x32x16_bf16 v[64:79], v[160:163], v[168:171], v[64:79]
	v_mfma_f32_32x32x16_bf16 v[48:63], v[164:167], v[168:171], v[48:63]
	s_branch .Lret_b0_end
